# up GEMM phase: meta-row tasks assigned to the workgroups that have no sixth tile
# speedup vs baseline: 1.0119x; 1.0119x over previous
.LBB0_944:
	v_readlane_b32 s0, v254, 46
	v_mov_b32_e32 v2, v148
	v_readlane_b32 s1, v254, 47
	s_andn2_b64 vcc, exec, s[0:1]
	v_readfirstlane_b32 s23, v2
	s_cbranch_vccnz .LBB0_952
	v_and_b32_e32 v3, 15, v2
	v_lshlrev_b32_e32 v0, 12, v3
	s_and_b32 s0, s23, 0xffffffc0
	v_lshl_add_u64 v[4:5], s[12:13], 0, v[0:1]
	v_lshrrev_b32_e32 v0, 1, v2
	s_ashr_i32 s26, s23, 3
	s_add_i32 s0, s0, 64
	v_and_b32_e32 v26, 24, v0
	s_and_b32 s14, s26, -8
	s_ashr_i32 s22, s0, 3
	v_lshlrev_b32_e32 v0, 1, v26
	v_lshl_add_u64 v[4:5], v[4:5], 0, v[0:1]
	s_mov_b64 s[0:1], 0x70000
	s_cmp_lt_i32 s14, s22
	v_lshl_add_u64 v[10:11], v[4:5], 0, s[0:1]
	v_lshl_add_u64 v[12:13], s[8:9], 0, v[0:1]
	v_lshlrev_b32_e32 v0, 1, v2
	v_and_b32_e32 v4, 3, v2
	s_cselect_b64 s[0:1], -1, 0
	s_lshl_b32 s8, s23, 5
	v_and_or_b32 v27, v0, 24, v4
	s_and_b32 s8, s8, 0xfffff800
	v_lshlrev_b32_e32 v0, 4, v2
	s_add_i32 s8, s8, 0
	v_and_b32_e32 v0, 0x3f0, v0
	v_add_u32_e32 v28, s8, v0
	v_add_u32_e32 v29, 0, v0
	v_mul_u32_u24_e32 v0, 0x5600, v3
	v_lshl_add_u64 v[2:3], s[6:7], 0, v[0:1]
	s_mov_b64 s[6:7], 0x25a000
	v_lshl_add_u64 v[14:15], v[2:3], 0, s[6:7]
	s_mov_b64 s[6:7], 0x300a000
	v_lshl_add_u64 v[16:17], v[2:3], 0, s[6:7]
	s_mov_b64 s[6:7], 0x5dba000
	s_cmp_lt_u32 s23, 64
	v_lshl_add_u64 v[18:19], v[2:3], 0, s[6:7]
	s_mov_b64 s[6:7], 0x8b6a000
	s_cselect_b64 s[8:9], -1, 0
	v_lshl_add_u64 v[20:21], v[2:3], 0, s[6:7]
	s_lshl_b32 s6, s26, 5
	s_and_b32 s12, s6, 0xffffff00
	s_sub_i32 s13, s2, 0x60
	s_cmp_lt_i32 s13, 0
	s_cbranch_scc1 .LBB0_952
	s_branch .LBB0_947
.LBB0_946:
	s_add_i32 s13, s13, 0xa0
	s_cmpk_lt_i32 s13, 0x158
	s_barrier
	s_cbranch_scc0 .LBB0_952
